# ff1 epilogue: output row addresses of row groups 1..7 advanced by a constant stride instead of a 64-bit multiply chain per group
# speedup vs baseline: 1.0047x; 1.0008x over previous
; DI unsigned cvtpk(float lo, float hi) { f32x2_t v = {lo, hi}; bf16x2_t b = __builtin_convertvector(v, bf16x2_t); return __builtin_bit_cast(unsigned, b); }
;     DI void operator()(const f32x4 (&acc)[2][2][4][2], const Unit& u, int wr, int wc, int fr, int fq) const {
;     ...
;             for (int m = 0; m < 4; ++m) { const int row = row0 + ai * HALF + m * 16; float sc = 1.f; if (SS) { if (invn > 0.f) { const f32x4 q4 = *(const f32x4*)(SS + (size_t)row * 4); sc = rsqrtf(((q4.x + q4.y) + (q4.z + q4.w)) * invn + EPS); } else sc = SS[row]; }
;                 bf16_t* rowp = O + (size_t)row * ldc + col0;
; #pragma unroll
;                 for (int bj = 0; bj < 2; ++bj) { f32x4 v0 = acc[ai][bj][m][0] * sc, v1 = acc[ai][bj][m][1] * sc;
;                     if (ACT == 1) {
; #pragma unroll
;                         for (int e = 0; e < 4; ++e) { const float a = fmaxf(v0[e], 0.f), b = fmaxf(v1[e], 0.f); v0[e] = a * a; v1[e] = b * b; } }
;                     u32x4 w; w.x = cvtpk(v0[0], v0[1]); w.y = cvtpk(v0[2], v0[3]); w.z = cvtpk(v1[0], v1[1]); w.w = cvtpk(v1[2], v1[3]);
;                     if (ACT == 1) __builtin_nontemporal_store(w, (u32x4*)(rowp + bj * HALF));
;                     else *(u32x4*)(rowp + bj * HALF) = w; }
;                 asm volatile("" ::: "memory"); }
.LBB0_695:
	v_mul_lo_u32 v135, s83, v130
	v_mul_lo_u32 v138, s82, v131
	v_mad_u64_u32 v[136:137], s[0:1], s82, v130, 0
	v_lshl_or_b32 v132, s65, 8, v244
	v_add3_u32 v137, v137, v138, v135
	v_ashrrev_i32_e32 v133, 31, v132
	v_lshl_add_u64 v[136:137], v[136:137], 1, s[84:85]
	v_lshl_add_u64 v[140:141], v[132:133], 1, v[136:137]
	v_mov_b64_e32 v[172:173], v[140:141]
	s_lshl_b64 s[0:1], s[82:83], 5
	v_mov_b32_e32 v174, s0
	v_mov_b32_e32 v175, s1
	s_mul_hi_u32 s1, s82, 0xa0
	s_mul_i32 s0, s82, 0xa0
	v_mov_b32_e32 v176, s0
	v_mov_b32_e32 v177, s1
	s_waitcnt vmcnt(0) lgkmcnt(0)
	v_pk_mul_f32 v[136:137], v[128:129], v[134:135] op_sel_hi:[1,0]
	v_pk_mul_f32 v[138:139], v[126:127], v[134:135] op_sel_hi:[1,0]
	v_pk_mul_f32 v[142:143], v[124:125], v[134:135] op_sel_hi:[1,0]
	v_pk_mul_f32 v[144:145], v[122:123], v[134:135] op_sel_hi:[1,0]
	v_max_f32_e32 v138, 0, v138
	v_max_f32_e32 v144, 0, v144
	v_max_f32_e32 v139, 0, v139
	v_max_f32_e32 v145, 0, v145
	v_max_f32_e32 v136, 0, v136
	v_max_f32_e32 v142, 0, v142
	v_max_f32_e32 v137, 0, v137
	v_max_f32_e32 v143, 0, v143
	v_pk_mul_f32 v[138:139], v[138:139], v[138:139]
	v_pk_mul_f32 v[144:145], v[144:145], v[144:145]
	v_pk_mul_f32 v[146:147], v[136:137], v[136:137]
	v_pk_mul_f32 v[142:143], v[142:143], v[142:143]
	v_cvt_pk_bf16_f32 v136, v138, v139
	v_cvt_pk_bf16_f32 v137, v146, v147
	v_cvt_pk_bf16_f32 v138, v144, v145
	v_cvt_pk_bf16_f32 v139, v142, v143
	flat_store_dwordx4 v[140:141], v[136:139] nt
	v_pk_mul_f32 v[142:143], v[116:117], v[134:135] op_sel_hi:[1,0]
	s_and_b64 vcc, exec, s[48:49]
	v_pk_mul_f32 v[136:137], v[120:121], v[134:135] op_sel_hi:[1,0]
	v_pk_mul_f32 v[138:139], v[118:119], v[134:135] op_sel_hi:[1,0]
	v_pk_mul_f32 v[134:135], v[114:115], v[134:135] op_sel_hi:[1,0]
	v_max_f32_e32 v138, 0, v138
	v_max_f32_e32 v134, 0, v134
	v_max_f32_e32 v135, 0, v135
	v_max_f32_e32 v139, 0, v139
	v_pk_mul_f32 v[144:145], v[134:135], v[134:135]
	v_max_f32_e32 v134, 0, v136
	v_max_f32_e32 v136, 0, v142
	v_max_f32_e32 v135, 0, v137
	v_max_f32_e32 v137, 0, v143
	v_pk_mul_f32 v[138:139], v[138:139], v[138:139]
	v_pk_mul_f32 v[142:143], v[134:135], v[134:135]
	v_pk_mul_f32 v[146:147], v[136:137], v[136:137]
	v_cvt_pk_bf16_f32 v134, v138, v139
	v_cvt_pk_bf16_f32 v135, v142, v143
	v_cvt_pk_bf16_f32 v136, v144, v145
	v_cvt_pk_bf16_f32 v137, v146, v147
	flat_store_dwordx4 v[140:141], v[134:137] offset:256 nt
	s_nop 1
	v_or_b32_e32 v134, 16, v130
	v_ashrrev_i32_e32 v135, 31, v134
	s_cbranch_vccnz .LBB0_700
	s_andn2_b64 vcc, exec, s[20:21]
	s_mov_b64 s[0:1], -1
	s_cbranch_vccnz .LBB0_698
	v_lshl_add_u64 v[136:137], v[130:131], 2, s[86:87]
	v_mov_b32_e32 v0, v148
	s_mov_b64 s[0:1], 0

; DI unsigned cvtpk(float lo, float hi) { f32x2_t v = {lo, hi}; bf16x2_t b = __builtin_convertvector(v, bf16x2_t); return __builtin_bit_cast(unsigned, b); }
;     DI void operator()(const f32x4 (&acc)[2][2][4][2], const Unit& u, int wr, int wc, int fr, int fq) const {
;     ...
;             for (int m = 0; m < 4; ++m) { const int row = row0 + ai * HALF + m * 16; float sc = 1.f; if (SS) { if (invn > 0.f) { const f32x4 q4 = *(const f32x4*)(SS + (size_t)row * 4); sc = rsqrtf(((q4.x + q4.y) + (q4.z + q4.w)) * invn + EPS); } else sc = SS[row]; }
;                 bf16_t* rowp = O + (size_t)row * ldc + col0;
; #pragma unroll
;                 for (int bj = 0; bj < 2; ++bj) { f32x4 v0 = acc[ai][bj][m][0] * sc, v1 = acc[ai][bj][m][1] * sc;
;                     if (ACT == 1) {
; #pragma unroll
;                         for (int e = 0; e < 4; ++e) { const float a = fmaxf(v0[e], 0.f), b = fmaxf(v1[e], 0.f); v0[e] = a * a; v1[e] = b * b; } }
;                     u32x4 w; w.x = cvtpk(v0[0], v0[1]); w.y = cvtpk(v0[2], v0[3]); w.z = cvtpk(v1[0], v1[1]); w.w = cvtpk(v1[2], v1[3]);
;                     if (ACT == 1) __builtin_nontemporal_store(w, (u32x4*)(rowp + bj * HALF));
;                     else *(u32x4*)(rowp + bj * HALF) = w; }
.LBB0_700:
	v_lshl_add_u64 v[172:173], v[172:173], 0, v[174:175]
	v_mov_b64_e32 v[138:139], v[172:173]
	v_pk_mul_f32 v[134:135], v[112:113], v[0:1] op_sel_hi:[1,0]
	v_pk_mul_f32 v[136:137], v[110:111], v[0:1] op_sel_hi:[1,0]
	v_pk_mul_f32 v[140:141], v[108:109], v[0:1] op_sel_hi:[1,0]
	v_pk_mul_f32 v[142:143], v[106:107], v[0:1] op_sel_hi:[1,0]
	v_max_f32_e32 v136, 0, v136
	v_max_f32_e32 v142, 0, v142
	v_max_f32_e32 v137, 0, v137
	v_max_f32_e32 v143, 0, v143
	v_max_f32_e32 v134, 0, v134
	v_max_f32_e32 v140, 0, v140
	v_max_f32_e32 v135, 0, v135
	v_max_f32_e32 v141, 0, v141
	v_pk_mul_f32 v[136:137], v[136:137], v[136:137]
	v_pk_mul_f32 v[142:143], v[142:143], v[142:143]
	v_pk_mul_f32 v[144:145], v[134:135], v[134:135]
	v_pk_mul_f32 v[140:141], v[140:141], v[140:141]
	v_cvt_pk_bf16_f32 v134, v136, v137
	v_cvt_pk_bf16_f32 v135, v144, v145
	v_cvt_pk_bf16_f32 v136, v142, v143
	v_cvt_pk_bf16_f32 v137, v140, v141
	flat_store_dwordx4 v[138:139], v[134:137] nt
	v_pk_mul_f32 v[140:141], v[100:101], v[0:1] op_sel_hi:[1,0]
	v_pk_mul_f32 v[142:143], v[98:99], v[0:1] op_sel_hi:[1,0]
	v_pk_mul_f32 v[134:135], v[104:105], v[0:1] op_sel_hi:[1,0]
	v_pk_mul_f32 v[136:137], v[102:103], v[0:1] op_sel_hi:[1,0]
	v_max_f32_e32 v142, 0, v142
	v_max_f32_e32 v136, 0, v136
	v_max_f32_e32 v137, 0, v137
	v_max_f32_e32 v143, 0, v143
	v_max_f32_e32 v134, 0, v134
	v_max_f32_e32 v140, 0, v140
	v_max_f32_e32 v135, 0, v135
	v_max_f32_e32 v141, 0, v141
	v_pk_mul_f32 v[136:137], v[136:137], v[136:137]
	v_pk_mul_f32 v[142:143], v[142:143], v[142:143]
	v_pk_mul_f32 v[144:145], v[134:135], v[134:135]
	v_pk_mul_f32 v[140:141], v[140:141], v[140:141]
	v_cvt_pk_bf16_f32 v134, v136, v137
	v_cvt_pk_bf16_f32 v135, v144, v145
	v_cvt_pk_bf16_f32 v136, v142, v143
	v_cvt_pk_bf16_f32 v137, v140, v141
	flat_store_dwordx4 v[138:139], v[134:137] offset:256 nt
	v_mov_b32_e32 v0, 1.0
	s_and_b64 vcc, exec, s[48:49]
	v_or_b32_e32 v136, 32, v130
	v_ashrrev_i32_e32 v137, 31, v136
	v_mov_b32_e32 v134, 1.0
	s_cbranch_vccnz .LBB0_705
	s_andn2_b64 vcc, exec, s[20:21]
	s_mov_b64 s[0:1], -1
	s_cbranch_vccnz .LBB0_703
	v_lshl_add_u64 v[134:135], v[130:131], 2, s[86:87]
	v_mov_b32_e32 v134, v149
	s_mov_b64 s[0:1], 0

; DI unsigned cvtpk(float lo, float hi) { f32x2_t v = {lo, hi}; bf16x2_t b = __builtin_convertvector(v, bf16x2_t); return __builtin_bit_cast(unsigned, b); }
;     DI void operator()(const f32x4 (&acc)[2][2][4][2], const Unit& u, int wr, int wc, int fr, int fq) const {
;     ...
;             for (int m = 0; m < 4; ++m) { const int row = row0 + ai * HALF + m * 16; float sc = 1.f; if (SS) { if (invn > 0.f) { const f32x4 q4 = *(const f32x4*)(SS + (size_t)row * 4); sc = rsqrtf(((q4.x + q4.y) + (q4.z + q4.w)) * invn + EPS); } else sc = SS[row]; }
;                 bf16_t* rowp = O + (size_t)row * ldc + col0;
; #pragma unroll
;                 for (int bj = 0; bj < 2; ++bj) { f32x4 v0 = acc[ai][bj][m][0] * sc, v1 = acc[ai][bj][m][1] * sc;
;                     if (ACT == 1) {
; #pragma unroll
;                         for (int e = 0; e < 4; ++e) { const float a = fmaxf(v0[e], 0.f), b = fmaxf(v1[e], 0.f); v0[e] = a * a; v1[e] = b * b; } }
;                     u32x4 w; w.x = cvtpk(v0[0], v0[1]); w.y = cvtpk(v0[2], v0[3]); w.z = cvtpk(v1[0], v1[1]); w.w = cvtpk(v1[2], v1[3]);
;                     if (ACT == 1) __builtin_nontemporal_store(w, (u32x4*)(rowp + bj * HALF));
;                     else *(u32x4*)(rowp + bj * HALF) = w; }
.LBB0_705:
	v_lshl_add_u64 v[172:173], v[172:173], 0, v[174:175]
	v_mov_b64_e32 v[140:141], v[172:173]
	v_pk_mul_f32 v[136:137], v[96:97], v[134:135] op_sel_hi:[1,0]
	v_pk_mul_f32 v[138:139], v[94:95], v[134:135] op_sel_hi:[1,0]
	v_pk_mul_f32 v[142:143], v[92:93], v[134:135] op_sel_hi:[1,0]
	v_pk_mul_f32 v[144:145], v[90:91], v[134:135] op_sel_hi:[1,0]
	v_max_f32_e32 v138, 0, v138
	v_max_f32_e32 v144, 0, v144
	v_max_f32_e32 v139, 0, v139
	v_max_f32_e32 v145, 0, v145
	v_max_f32_e32 v136, 0, v136
	v_max_f32_e32 v142, 0, v142
	v_max_f32_e32 v137, 0, v137
	v_max_f32_e32 v143, 0, v143
	v_pk_mul_f32 v[138:139], v[138:139], v[138:139]
	v_pk_mul_f32 v[144:145], v[144:145], v[144:145]
	v_pk_mul_f32 v[146:147], v[136:137], v[136:137]
	v_pk_mul_f32 v[142:143], v[142:143], v[142:143]
	v_cvt_pk_bf16_f32 v136, v138, v139
	v_cvt_pk_bf16_f32 v137, v146, v147
	v_cvt_pk_bf16_f32 v138, v144, v145
	v_cvt_pk_bf16_f32 v139, v142, v143
	flat_store_dwordx4 v[140:141], v[136:139] nt
	v_pk_mul_f32 v[142:143], v[84:85], v[134:135] op_sel_hi:[1,0]
	s_and_b64 vcc, exec, s[48:49]
	v_pk_mul_f32 v[136:137], v[88:89], v[134:135] op_sel_hi:[1,0]
	v_pk_mul_f32 v[138:139], v[86:87], v[134:135] op_sel_hi:[1,0]
	v_pk_mul_f32 v[134:135], v[82:83], v[134:135] op_sel_hi:[1,0]
	v_max_f32_e32 v138, 0, v138
	v_max_f32_e32 v134, 0, v134
	v_max_f32_e32 v135, 0, v135
	v_max_f32_e32 v139, 0, v139
	v_pk_mul_f32 v[144:145], v[134:135], v[134:135]
	v_max_f32_e32 v134, 0, v136
	v_max_f32_e32 v136, 0, v142
	v_max_f32_e32 v135, 0, v137
	v_max_f32_e32 v137, 0, v143
	v_pk_mul_f32 v[138:139], v[138:139], v[138:139]
	v_pk_mul_f32 v[142:143], v[134:135], v[134:135]
	v_pk_mul_f32 v[146:147], v[136:137], v[136:137]
	v_cvt_pk_bf16_f32 v134, v138, v139
	v_cvt_pk_bf16_f32 v135, v142, v143
	v_cvt_pk_bf16_f32 v136, v144, v145
	v_cvt_pk_bf16_f32 v137, v146, v147
	flat_store_dwordx4 v[140:141], v[134:137] offset:256 nt
	s_nop 1
	v_or_b32_e32 v134, 48, v130
	v_ashrrev_i32_e32 v135, 31, v134
	s_cbranch_vccnz .LBB0_710
	s_andn2_b64 vcc, exec, s[20:21]
	s_mov_b64 s[0:1], -1
	s_cbranch_vccnz .LBB0_708
	v_lshl_add_u64 v[136:137], v[130:131], 2, s[86:87]
	v_mov_b32_e32 v0, v150
	s_mov_b64 s[0:1], 0

; DI unsigned cvtpk(float lo, float hi) { f32x2_t v = {lo, hi}; bf16x2_t b = __builtin_convertvector(v, bf16x2_t); return __builtin_bit_cast(unsigned, b); }
;     DI void operator()(const f32x4 (&acc)[2][2][4][2], const Unit& u, int wr, int wc, int fr, int fq) const {
;     ...
;             for (int m = 0; m < 4; ++m) { const int row = row0 + ai * HALF + m * 16; float sc = 1.f; if (SS) { if (invn > 0.f) { const f32x4 q4 = *(const f32x4*)(SS + (size_t)row * 4); sc = rsqrtf(((q4.x + q4.y) + (q4.z + q4.w)) * invn + EPS); } else sc = SS[row]; }
;                 bf16_t* rowp = O + (size_t)row * ldc + col0;
; #pragma unroll
;                 for (int bj = 0; bj < 2; ++bj) { f32x4 v0 = acc[ai][bj][m][0] * sc, v1 = acc[ai][bj][m][1] * sc;
;                     if (ACT == 1) {
; #pragma unroll
;                         for (int e = 0; e < 4; ++e) { const float a = fmaxf(v0[e], 0.f), b = fmaxf(v1[e], 0.f); v0[e] = a * a; v1[e] = b * b; } }
;                     u32x4 w; w.x = cvtpk(v0[0], v0[1]); w.y = cvtpk(v0[2], v0[3]); w.z = cvtpk(v1[0], v1[1]); w.w = cvtpk(v1[2], v1[3]);
;                     if (ACT == 1) __builtin_nontemporal_store(w, (u32x4*)(rowp + bj * HALF));
;                     else *(u32x4*)(rowp + bj * HALF) = w; }
.LBB0_710:
	v_lshl_add_u64 v[172:173], v[172:173], 0, v[174:175]
	v_mov_b64_e32 v[138:139], v[172:173]
	v_pk_mul_f32 v[134:135], v[80:81], v[0:1] op_sel_hi:[1,0]
	v_pk_mul_f32 v[136:137], v[78:79], v[0:1] op_sel_hi:[1,0]
	v_pk_mul_f32 v[140:141], v[76:77], v[0:1] op_sel_hi:[1,0]
	v_pk_mul_f32 v[142:143], v[74:75], v[0:1] op_sel_hi:[1,0]
	v_max_f32_e32 v136, 0, v136
	v_max_f32_e32 v142, 0, v142
	v_max_f32_e32 v137, 0, v137
	v_max_f32_e32 v143, 0, v143
	v_max_f32_e32 v134, 0, v134
	v_max_f32_e32 v140, 0, v140
	v_max_f32_e32 v135, 0, v135
	v_max_f32_e32 v141, 0, v141
	v_pk_mul_f32 v[136:137], v[136:137], v[136:137]
	v_pk_mul_f32 v[142:143], v[142:143], v[142:143]
	v_pk_mul_f32 v[144:145], v[134:135], v[134:135]
	v_pk_mul_f32 v[140:141], v[140:141], v[140:141]
	v_cvt_pk_bf16_f32 v134, v136, v137
	v_cvt_pk_bf16_f32 v135, v144, v145
	v_cvt_pk_bf16_f32 v136, v142, v143
	v_cvt_pk_bf16_f32 v137, v140, v141
	flat_store_dwordx4 v[138:139], v[134:137] nt
	v_pk_mul_f32 v[140:141], v[68:69], v[0:1] op_sel_hi:[1,0]
	v_pk_mul_f32 v[142:143], v[66:67], v[0:1] op_sel_hi:[1,0]
	v_pk_mul_f32 v[134:135], v[72:73], v[0:1] op_sel_hi:[1,0]
	v_pk_mul_f32 v[136:137], v[70:71], v[0:1] op_sel_hi:[1,0]
	v_max_f32_e32 v142, 0, v142
	v_max_f32_e32 v136, 0, v136
	v_max_f32_e32 v137, 0, v137
	v_max_f32_e32 v143, 0, v143
	v_max_f32_e32 v134, 0, v134
	v_max_f32_e32 v140, 0, v140
	v_max_f32_e32 v135, 0, v135
	v_max_f32_e32 v141, 0, v141
	v_pk_mul_f32 v[136:137], v[136:137], v[136:137]
	v_pk_mul_f32 v[142:143], v[142:143], v[142:143]
	v_pk_mul_f32 v[144:145], v[134:135], v[134:135]
	v_pk_mul_f32 v[140:141], v[140:141], v[140:141]
	v_cvt_pk_bf16_f32 v134, v136, v137
	v_cvt_pk_bf16_f32 v135, v144, v145
	v_cvt_pk_bf16_f32 v136, v142, v143
	v_cvt_pk_bf16_f32 v137, v140, v141
	flat_store_dwordx4 v[138:139], v[134:137] offset:256 nt
	v_mov_b32_e32 v0, 1.0
	s_and_b64 vcc, exec, s[48:49]
	v_add_u32_e32 v136, 0x80, v130
	v_ashrrev_i32_e32 v137, 31, v136
	v_mov_b32_e32 v134, 1.0
	s_cbranch_vccnz .LBB0_715
	s_andn2_b64 vcc, exec, s[20:21]
	s_mov_b64 s[0:1], -1
	s_cbranch_vccnz .LBB0_713
	v_lshl_add_u64 v[134:135], v[130:131], 2, s[86:87]
	v_mov_b32_e32 v134, v151
	s_mov_b64 s[0:1], 0

; DI unsigned cvtpk(float lo, float hi) { f32x2_t v = {lo, hi}; bf16x2_t b = __builtin_convertvector(v, bf16x2_t); return __builtin_bit_cast(unsigned, b); }
;     DI void operator()(const f32x4 (&acc)[2][2][4][2], const Unit& u, int wr, int wc, int fr, int fq) const {
;     ...
;             for (int m = 0; m < 4; ++m) { const int row = row0 + ai * HALF + m * 16; float sc = 1.f; if (SS) { if (invn > 0.f) { const f32x4 q4 = *(const f32x4*)(SS + (size_t)row * 4); sc = rsqrtf(((q4.x + q4.y) + (q4.z + q4.w)) * invn + EPS); } else sc = SS[row]; }
;                 bf16_t* rowp = O + (size_t)row * ldc + col0;
; #pragma unroll
;                 for (int bj = 0; bj < 2; ++bj) { f32x4 v0 = acc[ai][bj][m][0] * sc, v1 = acc[ai][bj][m][1] * sc;
;                     if (ACT == 1) {
; #pragma unroll
;                         for (int e = 0; e < 4; ++e) { const float a = fmaxf(v0[e], 0.f), b = fmaxf(v1[e], 0.f); v0[e] = a * a; v1[e] = b * b; } }
;                     u32x4 w; w.x = cvtpk(v0[0], v0[1]); w.y = cvtpk(v0[2], v0[3]); w.z = cvtpk(v1[0], v1[1]); w.w = cvtpk(v1[2], v1[3]);
;                     if (ACT == 1) __builtin_nontemporal_store(w, (u32x4*)(rowp + bj * HALF));
;                     else *(u32x4*)(rowp + bj * HALF) = w; }
.LBB0_715:
	v_lshl_add_u64 v[172:173], v[172:173], 0, v[176:177]
	v_mov_b64_e32 v[140:141], v[172:173]
	v_pk_mul_f32 v[136:137], v[64:65], v[134:135] op_sel_hi:[1,0]
	v_pk_mul_f32 v[138:139], v[62:63], v[134:135] op_sel_hi:[1,0]
	v_pk_mul_f32 v[142:143], v[60:61], v[134:135] op_sel_hi:[1,0]
	v_pk_mul_f32 v[144:145], v[58:59], v[134:135] op_sel_hi:[1,0]
	v_max_f32_e32 v138, 0, v138
	v_max_f32_e32 v144, 0, v144
	v_max_f32_e32 v139, 0, v139
	v_max_f32_e32 v145, 0, v145
	v_max_f32_e32 v136, 0, v136
	v_max_f32_e32 v142, 0, v142
	v_max_f32_e32 v137, 0, v137
	v_max_f32_e32 v143, 0, v143
	v_pk_mul_f32 v[138:139], v[138:139], v[138:139]
	v_pk_mul_f32 v[144:145], v[144:145], v[144:145]
	v_pk_mul_f32 v[146:147], v[136:137], v[136:137]
	v_pk_mul_f32 v[142:143], v[142:143], v[142:143]
	v_cvt_pk_bf16_f32 v136, v138, v139
	v_cvt_pk_bf16_f32 v137, v146, v147
	v_cvt_pk_bf16_f32 v138, v144, v145
	v_cvt_pk_bf16_f32 v139, v142, v143
	flat_store_dwordx4 v[140:141], v[136:139] nt
	v_pk_mul_f32 v[142:143], v[52:53], v[134:135] op_sel_hi:[1,0]
	s_and_b64 vcc, exec, s[48:49]
	v_pk_mul_f32 v[136:137], v[56:57], v[134:135] op_sel_hi:[1,0]
	v_pk_mul_f32 v[138:139], v[54:55], v[134:135] op_sel_hi:[1,0]
	v_pk_mul_f32 v[134:135], v[50:51], v[134:135] op_sel_hi:[1,0]
	v_max_f32_e32 v138, 0, v138
	v_max_f32_e32 v134, 0, v134
	v_max_f32_e32 v135, 0, v135
	v_max_f32_e32 v139, 0, v139
	v_pk_mul_f32 v[144:145], v[134:135], v[134:135]
	v_max_f32_e32 v134, 0, v136
	v_max_f32_e32 v136, 0, v142
	v_max_f32_e32 v135, 0, v137
	v_max_f32_e32 v137, 0, v143
	v_pk_mul_f32 v[138:139], v[138:139], v[138:139]
	v_pk_mul_f32 v[142:143], v[134:135], v[134:135]
	v_pk_mul_f32 v[146:147], v[136:137], v[136:137]
	v_cvt_pk_bf16_f32 v134, v138, v139
	v_cvt_pk_bf16_f32 v135, v142, v143
	v_cvt_pk_bf16_f32 v136, v144, v145
	v_cvt_pk_bf16_f32 v137, v146, v147
	flat_store_dwordx4 v[140:141], v[134:137] offset:256 nt
	s_nop 1
	v_add_u32_e32 v134, 0x90, v130
	v_ashrrev_i32_e32 v135, 31, v134
	s_cbranch_vccnz .LBB0_720
	s_andn2_b64 vcc, exec, s[20:21]
	s_mov_b64 s[0:1], -1
	s_cbranch_vccnz .LBB0_718
	v_lshl_add_u64 v[136:137], v[130:131], 2, s[86:87]
	v_mov_b32_e32 v0, v152
	s_mov_b64 s[0:1], 0

; DI unsigned cvtpk(float lo, float hi) { f32x2_t v = {lo, hi}; bf16x2_t b = __builtin_convertvector(v, bf16x2_t); return __builtin_bit_cast(unsigned, b); }
;     DI void operator()(const f32x4 (&acc)[2][2][4][2], const Unit& u, int wr, int wc, int fr, int fq) const {
;     ...
;             for (int m = 0; m < 4; ++m) { const int row = row0 + ai * HALF + m * 16; float sc = 1.f; if (SS) { if (invn > 0.f) { const f32x4 q4 = *(const f32x4*)(SS + (size_t)row * 4); sc = rsqrtf(((q4.x + q4.y) + (q4.z + q4.w)) * invn + EPS); } else sc = SS[row]; }
;                 bf16_t* rowp = O + (size_t)row * ldc + col0;
; #pragma unroll
;                 for (int bj = 0; bj < 2; ++bj) { f32x4 v0 = acc[ai][bj][m][0] * sc, v1 = acc[ai][bj][m][1] * sc;
;                     if (ACT == 1) {
; #pragma unroll
;                         for (int e = 0; e < 4; ++e) { const float a = fmaxf(v0[e], 0.f), b = fmaxf(v1[e], 0.f); v0[e] = a * a; v1[e] = b * b; } }
;                     u32x4 w; w.x = cvtpk(v0[0], v0[1]); w.y = cvtpk(v0[2], v0[3]); w.z = cvtpk(v1[0], v1[1]); w.w = cvtpk(v1[2], v1[3]);
;                     if (ACT == 1) __builtin_nontemporal_store(w, (u32x4*)(rowp + bj * HALF));
;                     else *(u32x4*)(rowp + bj * HALF) = w; }
.LBB0_720:
	v_lshl_add_u64 v[172:173], v[172:173], 0, v[174:175]
	v_mov_b64_e32 v[138:139], v[172:173]
	v_pk_mul_f32 v[134:135], v[48:49], v[0:1] op_sel_hi:[1,0]
	v_pk_mul_f32 v[136:137], v[46:47], v[0:1] op_sel_hi:[1,0]
	v_pk_mul_f32 v[140:141], v[44:45], v[0:1] op_sel_hi:[1,0]
	v_pk_mul_f32 v[142:143], v[42:43], v[0:1] op_sel_hi:[1,0]
	v_max_f32_e32 v136, 0, v136
	v_max_f32_e32 v142, 0, v142
	v_max_f32_e32 v137, 0, v137
	v_max_f32_e32 v143, 0, v143
	v_max_f32_e32 v134, 0, v134
	v_max_f32_e32 v140, 0, v140
	v_max_f32_e32 v135, 0, v135
	v_max_f32_e32 v141, 0, v141
	v_pk_mul_f32 v[136:137], v[136:137], v[136:137]
	v_pk_mul_f32 v[142:143], v[142:143], v[142:143]
	v_pk_mul_f32 v[144:145], v[134:135], v[134:135]
	v_pk_mul_f32 v[140:141], v[140:141], v[140:141]
	v_cvt_pk_bf16_f32 v134, v136, v137
	v_cvt_pk_bf16_f32 v135, v144, v145
	v_cvt_pk_bf16_f32 v136, v142, v143
	v_cvt_pk_bf16_f32 v137, v140, v141
	flat_store_dwordx4 v[138:139], v[134:137] nt
	v_pk_mul_f32 v[140:141], v[36:37], v[0:1] op_sel_hi:[1,0]
	v_pk_mul_f32 v[142:143], v[34:35], v[0:1] op_sel_hi:[1,0]
	v_pk_mul_f32 v[134:135], v[40:41], v[0:1] op_sel_hi:[1,0]
	v_pk_mul_f32 v[136:137], v[38:39], v[0:1] op_sel_hi:[1,0]
	v_max_f32_e32 v142, 0, v142
	v_max_f32_e32 v136, 0, v136
	v_max_f32_e32 v137, 0, v137
	v_max_f32_e32 v143, 0, v143
	v_max_f32_e32 v134, 0, v134
	v_max_f32_e32 v140, 0, v140
	v_max_f32_e32 v135, 0, v135
	v_max_f32_e32 v141, 0, v141
	v_pk_mul_f32 v[136:137], v[136:137], v[136:137]
	v_pk_mul_f32 v[142:143], v[142:143], v[142:143]
	v_pk_mul_f32 v[144:145], v[134:135], v[134:135]
	v_pk_mul_f32 v[140:141], v[140:141], v[140:141]
	v_cvt_pk_bf16_f32 v134, v136, v137
	v_cvt_pk_bf16_f32 v135, v144, v145
	v_cvt_pk_bf16_f32 v136, v142, v143
	v_cvt_pk_bf16_f32 v137, v140, v141
	flat_store_dwordx4 v[138:139], v[134:137] offset:256 nt
	v_mov_b32_e32 v0, 1.0
	s_and_b64 vcc, exec, s[48:49]
	v_add_u32_e32 v136, 0xa0, v130
	v_ashrrev_i32_e32 v137, 31, v136
	v_mov_b32_e32 v134, 1.0
	s_cbranch_vccnz .LBB0_725
	s_andn2_b64 vcc, exec, s[20:21]
	s_mov_b64 s[0:1], -1
	s_cbranch_vccnz .LBB0_723
	v_lshl_add_u64 v[134:135], v[130:131], 2, s[86:87]
	v_mov_b32_e32 v134, v153
	s_mov_b64 s[0:1], 0

; DI unsigned cvtpk(float lo, float hi) { f32x2_t v = {lo, hi}; bf16x2_t b = __builtin_convertvector(v, bf16x2_t); return __builtin_bit_cast(unsigned, b); }
;     DI void operator()(const f32x4 (&acc)[2][2][4][2], const Unit& u, int wr, int wc, int fr, int fq) const {
;     ...
;             for (int m = 0; m < 4; ++m) { const int row = row0 + ai * HALF + m * 16; float sc = 1.f; if (SS) { if (invn > 0.f) { const f32x4 q4 = *(const f32x4*)(SS + (size_t)row * 4); sc = rsqrtf(((q4.x + q4.y) + (q4.z + q4.w)) * invn + EPS); } else sc = SS[row]; }
;                 bf16_t* rowp = O + (size_t)row * ldc + col0;
; #pragma unroll
;                 for (int bj = 0; bj < 2; ++bj) { f32x4 v0 = acc[ai][bj][m][0] * sc, v1 = acc[ai][bj][m][1] * sc;
;                     if (ACT == 1) {
; #pragma unroll
;                         for (int e = 0; e < 4; ++e) { const float a = fmaxf(v0[e], 0.f), b = fmaxf(v1[e], 0.f); v0[e] = a * a; v1[e] = b * b; } }
;                     u32x4 w; w.x = cvtpk(v0[0], v0[1]); w.y = cvtpk(v0[2], v0[3]); w.z = cvtpk(v1[0], v1[1]); w.w = cvtpk(v1[2], v1[3]);
;                     if (ACT == 1) __builtin_nontemporal_store(w, (u32x4*)(rowp + bj * HALF));
;                     else *(u32x4*)(rowp + bj * HALF) = w; }
;                 asm volatile("" ::: "memory"); }
.LBB0_725:
	v_lshl_add_u64 v[172:173], v[172:173], 0, v[174:175]
	v_mov_b64_e32 v[140:141], v[172:173]
	v_pk_mul_f32 v[136:137], v[32:33], v[134:135] op_sel_hi:[1,0]
	v_pk_mul_f32 v[138:139], v[30:31], v[134:135] op_sel_hi:[1,0]
	v_pk_mul_f32 v[142:143], v[28:29], v[134:135] op_sel_hi:[1,0]
	v_pk_mul_f32 v[144:145], v[26:27], v[134:135] op_sel_hi:[1,0]
	v_max_f32_e32 v138, 0, v138
	v_max_f32_e32 v144, 0, v144
	v_max_f32_e32 v139, 0, v139
	v_max_f32_e32 v145, 0, v145
	v_max_f32_e32 v136, 0, v136
	v_max_f32_e32 v142, 0, v142
	v_max_f32_e32 v137, 0, v137
	v_max_f32_e32 v143, 0, v143
	v_pk_mul_f32 v[138:139], v[138:139], v[138:139]
	v_pk_mul_f32 v[144:145], v[144:145], v[144:145]
	v_pk_mul_f32 v[146:147], v[136:137], v[136:137]
	v_pk_mul_f32 v[142:143], v[142:143], v[142:143]
	v_cvt_pk_bf16_f32 v136, v138, v139
	v_cvt_pk_bf16_f32 v137, v146, v147
	v_cvt_pk_bf16_f32 v138, v144, v145
	v_cvt_pk_bf16_f32 v139, v142, v143
	flat_store_dwordx4 v[140:141], v[136:139] nt
	v_pk_mul_f32 v[142:143], v[20:21], v[134:135] op_sel_hi:[1,0]
	s_and_b64 vcc, exec, s[48:49]
	v_pk_mul_f32 v[136:137], v[24:25], v[134:135] op_sel_hi:[1,0]
	v_pk_mul_f32 v[138:139], v[22:23], v[134:135] op_sel_hi:[1,0]
	v_pk_mul_f32 v[134:135], v[18:19], v[134:135] op_sel_hi:[1,0]
	v_max_f32_e32 v138, 0, v138
	v_max_f32_e32 v134, 0, v134
	v_max_f32_e32 v135, 0, v135
	v_max_f32_e32 v139, 0, v139
	v_pk_mul_f32 v[144:145], v[134:135], v[134:135]
	v_max_f32_e32 v134, 0, v136
	v_max_f32_e32 v136, 0, v142
	v_max_f32_e32 v135, 0, v137
	v_max_f32_e32 v137, 0, v143
	v_pk_mul_f32 v[138:139], v[138:139], v[138:139]
	v_pk_mul_f32 v[142:143], v[134:135], v[134:135]
	v_pk_mul_f32 v[146:147], v[136:137], v[136:137]
	v_cvt_pk_bf16_f32 v134, v138, v139
	v_cvt_pk_bf16_f32 v135, v142, v143
	v_cvt_pk_bf16_f32 v136, v144, v145
	v_cvt_pk_bf16_f32 v137, v146, v147
	flat_store_dwordx4 v[140:141], v[134:137] offset:256 nt
	s_nop 1
	v_add_u32_e32 v134, 0xb0, v130
	v_ashrrev_i32_e32 v135, 31, v134
	s_cbranch_vccnz .LBB0_730
	s_andn2_b64 vcc, exec, s[20:21]
	s_mov_b64 s[0:1], -1
	s_cbranch_vccnz .LBB0_728
	v_lshl_add_u64 v[136:137], v[130:131], 2, s[86:87]
	v_mov_b32_e32 v0, v154
	s_mov_b64 s[0:1], 0

; DI unsigned cvtpk(float lo, float hi) { f32x2_t v = {lo, hi}; bf16x2_t b = __builtin_convertvector(v, bf16x2_t); return __builtin_bit_cast(unsigned, b); }
;     DI void operator()(const f32x4 (&acc)[2][2][4][2], const Unit& u, int wr, int wc, int fr, int fq) const {
;     ...
;             for (int m = 0; m < 4; ++m) { const int row = row0 + ai * HALF + m * 16; float sc = 1.f; if (SS) { if (invn > 0.f) { const f32x4 q4 = *(const f32x4*)(SS + (size_t)row * 4); sc = rsqrtf(((q4.x + q4.y) + (q4.z + q4.w)) * invn + EPS); } else sc = SS[row]; }
;                 bf16_t* rowp = O + (size_t)row * ldc + col0;
; #pragma unroll
;                 for (int bj = 0; bj < 2; ++bj) { f32x4 v0 = acc[ai][bj][m][0] * sc, v1 = acc[ai][bj][m][1] * sc;
;                     if (ACT == 1) {
; #pragma unroll
;                         for (int e = 0; e < 4; ++e) { const float a = fmaxf(v0[e], 0.f), b = fmaxf(v1[e], 0.f); v0[e] = a * a; v1[e] = b * b; } }
;                     u32x4 w; w.x = cvtpk(v0[0], v0[1]); w.y = cvtpk(v0[2], v0[3]); w.z = cvtpk(v1[0], v1[1]); w.w = cvtpk(v1[2], v1[3]);
;                     if (ACT == 1) __builtin_nontemporal_store(w, (u32x4*)(rowp + bj * HALF));
;                     else *(u32x4*)(rowp + bj * HALF) = w; }
;                 asm volatile("" ::: "memory"); }
.LBB0_730:
	v_lshl_add_u64 v[172:173], v[172:173], 0, v[174:175]
	v_mov_b64_e32 v[136:137], v[172:173]
	v_pk_mul_f32 v[132:133], v[16:17], v[0:1] op_sel_hi:[1,0]
	v_pk_mul_f32 v[134:135], v[14:15], v[0:1] op_sel_hi:[1,0]
	v_pk_mul_f32 v[138:139], v[12:13], v[0:1] op_sel_hi:[1,0]
	v_pk_mul_f32 v[140:141], v[10:11], v[0:1] op_sel_hi:[1,0]
	v_max_f32_e32 v134, 0, v134
	v_max_f32_e32 v140, 0, v140
	v_max_f32_e32 v135, 0, v135
	v_max_f32_e32 v141, 0, v141
	v_max_f32_e32 v132, 0, v132
	v_max_f32_e32 v138, 0, v138
	v_max_f32_e32 v133, 0, v133
	v_max_f32_e32 v139, 0, v139
	v_pk_mul_f32 v[134:135], v[134:135], v[134:135]
	v_pk_mul_f32 v[140:141], v[140:141], v[140:141]
	v_pk_mul_f32 v[142:143], v[132:133], v[132:133]
	v_pk_mul_f32 v[138:139], v[138:139], v[138:139]
	v_cvt_pk_bf16_f32 v132, v134, v135
	v_cvt_pk_bf16_f32 v133, v142, v143
	v_cvt_pk_bf16_f32 v134, v140, v141
	v_cvt_pk_bf16_f32 v135, v138, v139
	flat_store_dwordx4 v[136:137], v[132:135] nt
	v_pk_mul_f32 v[138:139], v[4:5], v[0:1] op_sel_hi:[1,0]
	v_pk_mul_f32 v[140:141], v[2:3], v[0:1] op_sel_hi:[1,0]
	v_pk_mul_f32 v[132:133], v[8:9], v[0:1] op_sel_hi:[1,0]
	v_pk_mul_f32 v[134:135], v[6:7], v[0:1] op_sel_hi:[1,0]
	v_max_f32_e32 v140, 0, v140
	v_max_f32_e32 v134, 0, v134
	v_max_f32_e32 v135, 0, v135
	v_max_f32_e32 v141, 0, v141
	v_max_f32_e32 v132, 0, v132
	v_max_f32_e32 v138, 0, v138
	v_max_f32_e32 v133, 0, v133
	v_max_f32_e32 v139, 0, v139
	v_pk_mul_f32 v[134:135], v[134:135], v[134:135]
	v_pk_mul_f32 v[140:141], v[140:141], v[140:141]
	v_pk_mul_f32 v[142:143], v[132:133], v[132:133]
	v_pk_mul_f32 v[138:139], v[138:139], v[138:139]
	v_cvt_pk_bf16_f32 v132, v134, v135
	v_cvt_pk_bf16_f32 v133, v142, v143
	v_cvt_pk_bf16_f32 v134, v140, v141
	v_cvt_pk_bf16_f32 v135, v138, v139
	flat_store_dwordx4 v[136:137], v[132:135] offset:256 nt
	s_mov_b64 s[0:1], 0
